# v19: nt on LN x-row stores and on the out-epilogue residual loads (streams not re-read soon)
# speedup vs baseline: 1.0492x; 1.0005x over previous
.LBB0_14:
	v_ashrrev_i32_e32 v0, 12, v0
	v_add_u32_e32 v0, 1, v0
	v_cndmask_b32_e64 v0, v0, 0, s[8:9]
	s_load_dwordx2 s[8:9], s[0:1], 0xe8
	s_mul_i32 s10, s74, 9
	v_add_u32_e32 v0, s10, v0
	v_mov_b32_e32 v121, v1
	v_mov_b32_e32 v123, v1
	s_waitcnt lgkmcnt(0)
	v_lshl_add_u64 v[68:69], s[8:9], 0, v[70:71]
	s_load_dwordx2 s[8:9], s[0:1], 0x188
	s_mov_b64 s[24:25], -1
	s_waitcnt lgkmcnt(0)
	v_mov_b64_e32 v[70:71], s[8:9]
	v_mad_i64_i32 v[70:71], s[8:9], v0, s87, v[70:71]
	v_lshl_add_u64 v[70:71], s[22:23], 2, v[70:71]
	v_lshl_add_u64 v[70:71], v[70:71], 0, v[120:121]
	v_lshl_add_u64 v[70:71], v[70:71], 0, v[122:123]
	s_mov_b64 s[8:9], 0x2000
	v_lshl_add_u64 v[72:73], v[70:71], 0, s[8:9]
	s_movk_i32 s8, 0x2000
	v_add_co_u32_e32 v70, vcc, s8, v70
	s_nop 1
	v_addc_co_u32_e32 v71, vcc, 0, v71, vcc
	global_load_dword v0, v[70:71], off
	s_nop 0
	global_load_dword v72, v[72:73], off offset:64
	v_mov_b32_e32 v71, s23
	v_or_b32_e32 v70, s22, v86
	s_and_b64 vcc, exec, s[20:21]
	v_lshl_add_u64 v[152:153], v[70:71], 0, v[88:89]
	v_lshlrev_b64 v[152:153], 2, v[152:153]
	v_lshl_add_u64 v[152:153], v[66:67], 0, v[152:153]
	global_load_dwordx4 v[152:155], v[152:153], off nt
	v_lshl_add_u64 v[156:157], v[70:71], 0, v[90:91]
	v_lshlrev_b64 v[156:157], 2, v[156:157]
	v_lshl_add_u64 v[156:157], v[66:67], 0, v[156:157]
	global_load_dwordx4 v[156:159], v[156:157], off nt
	v_lshl_add_u64 v[160:161], v[70:71], 0, v[92:93]
	v_lshlrev_b64 v[160:161], 2, v[160:161]
	v_lshl_add_u64 v[160:161], v[66:67], 0, v[160:161]
	global_load_dwordx4 v[160:163], v[160:161], off nt
	v_lshl_add_u64 v[164:165], v[70:71], 0, v[94:95]
	v_lshlrev_b64 v[164:165], 2, v[164:165]
	v_lshl_add_u64 v[164:165], v[66:67], 0, v[164:165]
	global_load_dwordx4 v[164:167], v[164:165], off nt
	v_lshl_add_u64 v[168:169], v[70:71], 0, v[96:97]
	v_lshlrev_b64 v[168:169], 2, v[168:169]
	v_lshl_add_u64 v[168:169], v[66:67], 0, v[168:169]
	global_load_dwordx4 v[168:171], v[168:169], off nt
	v_lshl_add_u64 v[172:173], v[70:71], 0, v[98:99]
	v_lshlrev_b64 v[172:173], 2, v[172:173]
	v_lshl_add_u64 v[172:173], v[66:67], 0, v[172:173]
	global_load_dwordx4 v[172:175], v[172:173], off nt
	v_lshl_add_u64 v[176:177], v[70:71], 0, v[100:101]
	v_lshlrev_b64 v[176:177], 2, v[176:177]
	v_lshl_add_u64 v[176:177], v[66:67], 0, v[176:177]
	global_load_dwordx4 v[176:179], v[176:177], off nt
	v_lshl_add_u64 v[180:181], v[70:71], 0, v[102:103]
	v_lshlrev_b64 v[180:181], 2, v[180:181]
	v_lshl_add_u64 v[180:181], v[66:67], 0, v[180:181]
	global_load_dwordx4 v[180:183], v[180:181], off nt
	v_lshl_add_u64 v[184:185], v[70:71], 0, v[104:105]
	v_lshlrev_b64 v[184:185], 2, v[184:185]
	v_lshl_add_u64 v[184:185], v[66:67], 0, v[184:185]
	global_load_dwordx4 v[184:187], v[184:185], off nt
	v_lshl_add_u64 v[188:189], v[70:71], 0, v[106:107]
	v_lshlrev_b64 v[188:189], 2, v[188:189]
	v_lshl_add_u64 v[188:189], v[66:67], 0, v[188:189]
	global_load_dwordx4 v[188:191], v[188:189], off nt
	v_lshl_add_u64 v[192:193], v[70:71], 0, v[108:109]
	v_lshlrev_b64 v[192:193], 2, v[192:193]
	v_lshl_add_u64 v[192:193], v[66:67], 0, v[192:193]
	global_load_dwordx4 v[192:195], v[192:193], off nt
	v_lshl_add_u64 v[196:197], v[70:71], 0, v[110:111]
	v_lshlrev_b64 v[196:197], 2, v[196:197]
	v_lshl_add_u64 v[196:197], v[66:67], 0, v[196:197]
	global_load_dwordx4 v[196:199], v[196:197], off nt
	v_lshl_add_u64 v[200:201], v[70:71], 0, v[112:113]
	v_lshlrev_b64 v[200:201], 2, v[200:201]
	v_lshl_add_u64 v[200:201], v[66:67], 0, v[200:201]
	global_load_dwordx4 v[200:203], v[200:201], off nt
	v_lshl_add_u64 v[204:205], v[70:71], 0, v[114:115]
	v_lshlrev_b64 v[204:205], 2, v[204:205]
	v_lshl_add_u64 v[204:205], v[66:67], 0, v[204:205]
	global_load_dwordx4 v[204:207], v[204:205], off nt
	v_lshl_add_u64 v[208:209], v[70:71], 0, v[116:117]
	v_lshlrev_b64 v[208:209], 2, v[208:209]
	v_lshl_add_u64 v[208:209], v[66:67], 0, v[208:209]
	global_load_dwordx4 v[208:211], v[208:209], off nt
	v_lshl_add_u64 v[74:75], v[70:71], 0, v[118:119]
	v_lshlrev_b64 v[74:75], 2, v[74:75]
	v_lshl_add_u64 v[74:75], v[66:67], 0, v[74:75]
	global_load_dwordx4 v[74:77], v[74:75], off nt
	s_waitcnt vmcnt(16)
	v_mul_f32_e32 v62, v62, v0
	v_mul_f32_e32 v58, v58, v72
	ds_write2_b32 v136, v62, v58 offset1:16
	v_mul_f32_e32 v58, v63, v0
	v_mul_f32_e32 v59, v59, v72
	ds_write2_b32 v136, v58, v59 offset0:36 offset1:52
	v_mul_f32_e32 v58, v64, v0
	v_mul_f32_e32 v59, v60, v72
	ds_write2_b32 v136, v58, v59 offset0:72 offset1:88
	v_mul_f32_e32 v58, v65, v0
	v_mul_f32_e32 v59, v61, v72
	ds_write2_b32 v136, v58, v59 offset0:108 offset1:124
	v_mul_f32_e32 v54, v54, v0
	v_mul_f32_e32 v58, v50, v72
	v_add_u32_e32 v50, 0x800, v136
	ds_write2_b32 v50, v54, v58 offset0:64 offset1:80
	v_mul_f32_e32 v54, v55, v0
	v_mul_f32_e32 v51, v51, v72
	ds_write2_b32 v50, v54, v51 offset0:100 offset1:116
	v_mul_f32_e32 v51, v56, v0
	v_mul_f32_e32 v52, v52, v72
	ds_write2_b32 v50, v51, v52 offset0:136 offset1:152
	v_mul_f32_e32 v51, v57, v0
	v_mul_f32_e32 v52, v53, v72
	v_lshl_add_u64 v[56:57], v[70:71], 0, v[88:89]
	ds_write2_b32 v50, v51, v52 offset0:172 offset1:188
	v_lshlrev_b64 v[60:61], 2, v[56:57]
	s_waitcnt lgkmcnt(0)
	v_lshl_add_u64 v[56:57], v[66:67], 0, v[60:61]
	ds_read_b128 v[52:55], v137
	v_mul_f32_e32 v46, v46, v0
	v_mul_f32_e32 v42, v42, v72
	v_mul_f32_e32 v38, v38, v0
	v_mul_f32_e32 v34, v34, v72
	v_mul_f32_e32 v43, v43, v72
	v_mul_f32_e32 v35, v35, v72
	v_mul_f32_e32 v30, v30, v0
	v_mul_f32_e32 v26, v26, v72
	v_mul_f32_e32 v22, v22, v0
	v_mul_f32_e32 v18, v18, v72
	v_mul_f32_e32 v27, v27, v72
	v_mul_f32_e32 v19, v19, v72
	v_mul_f32_e32 v14, v14, v0
	v_mul_f32_e32 v10, v10, v72
	v_mul_f32_e32 v6, v6, v0
	v_mul_f32_e32 v2, v2, v72
	v_mul_f32_e32 v11, v11, v72
	v_mul_f32_e32 v3, v3, v72
	s_waitcnt vmcnt(15) lgkmcnt(0)
	v_pk_fma_f32 v[54:55], v[154:155], s[98:99], v[54:55] op_sel_hi:[1,0,1]
	v_pk_fma_f32 v[52:53], v[152:153], s[98:99], v[52:53] op_sel_hi:[1,0,1]
	v_lshl_add_u64 v[56:57], v[68:69], 0, v[60:61]
	global_store_dwordx4 v[56:57], v[52:55], off sc0 sc1
	v_lshl_add_u64 v[56:57], v[70:71], 0, v[90:91]
	v_lshlrev_b64 v[60:61], 2, v[56:57]
	v_lshl_add_u64 v[56:57], v[66:67], 0, v[60:61]
	ds_read_b128 v[52:55], v138
	s_waitcnt vmcnt(15) lgkmcnt(0)
	v_pk_fma_f32 v[54:55], v[158:159], s[98:99], v[54:55] op_sel_hi:[1,0,1]
	v_pk_fma_f32 v[52:53], v[156:157], s[98:99], v[52:53] op_sel_hi:[1,0,1]
	v_lshl_add_u64 v[56:57], v[68:69], 0, v[60:61]
	global_store_dwordx4 v[56:57], v[52:55], off sc0 sc1
	v_lshl_add_u64 v[56:57], v[70:71], 0, v[92:93]
	v_lshlrev_b64 v[60:61], 2, v[56:57]
	v_lshl_add_u64 v[56:57], v[66:67], 0, v[60:61]
	ds_read_b128 v[52:55], v139
	s_waitcnt vmcnt(15) lgkmcnt(0)
	v_pk_fma_f32 v[54:55], v[162:163], s[98:99], v[54:55] op_sel_hi:[1,0,1]
	v_pk_fma_f32 v[52:53], v[160:161], s[98:99], v[52:53] op_sel_hi:[1,0,1]
	v_lshl_add_u64 v[56:57], v[68:69], 0, v[60:61]
	global_store_dwordx4 v[56:57], v[52:55], off sc0 sc1
	v_lshl_add_u64 v[56:57], v[70:71], 0, v[94:95]
	v_lshlrev_b64 v[60:61], 2, v[56:57]
	v_lshl_add_u64 v[56:57], v[66:67], 0, v[60:61]
	ds_read_b128 v[52:55], v140
	s_waitcnt vmcnt(15) lgkmcnt(0)
	v_pk_fma_f32 v[54:55], v[166:167], s[98:99], v[54:55] op_sel_hi:[1,0,1]
	v_pk_fma_f32 v[52:53], v[164:165], s[98:99], v[52:53] op_sel_hi:[1,0,1]
	v_lshl_add_u64 v[56:57], v[68:69], 0, v[60:61]
	global_store_dwordx4 v[56:57], v[52:55], off sc0 sc1
	s_waitcnt lgkmcnt(0)
	ds_write2_b32 v136, v46, v42 offset1:16
	v_mul_f32_e32 v42, v47, v0
	ds_write2_b32 v50, v38, v34 offset0:64 offset1:80
	v_mul_f32_e32 v34, v39, v0
	ds_write2_b32 v136, v42, v43 offset0:36 offset1:52
	v_mul_f32_e32 v42, v48, v0
	v_mul_f32_e32 v43, v44, v72
	ds_write2_b32 v50, v34, v35 offset0:100 offset1:116
	v_mul_f32_e32 v34, v40, v0
	v_mul_f32_e32 v35, v36, v72
	ds_write2_b32 v136, v42, v43 offset0:72 offset1:88
	v_mul_f32_e32 v42, v49, v0
	v_mul_f32_e32 v43, v45, v72
	ds_write2_b32 v50, v34, v35 offset0:136 offset1:152
	v_mul_f32_e32 v34, v41, v0
	v_mul_f32_e32 v35, v37, v72
	v_lshl_add_u64 v[38:39], v[70:71], 0, v[96:97]
	ds_write2_b32 v136, v42, v43 offset0:108 offset1:124
	ds_write2_b32 v50, v34, v35 offset0:172 offset1:188
	v_lshlrev_b64 v[42:43], 2, v[38:39]
	s_waitcnt lgkmcnt(0)
	v_lshl_add_u64 v[38:39], v[66:67], 0, v[42:43]
	ds_read_b128 v[34:37], v137
	s_waitcnt vmcnt(15) lgkmcnt(0)
	v_pk_fma_f32 v[36:37], v[170:171], s[98:99], v[36:37] op_sel_hi:[1,0,1]
	v_pk_fma_f32 v[34:35], v[168:169], s[98:99], v[34:35] op_sel_hi:[1,0,1]
	v_lshl_add_u64 v[38:39], v[68:69], 0, v[42:43]
	global_store_dwordx4 v[38:39], v[34:37], off sc0 sc1
	v_lshl_add_u64 v[38:39], v[70:71], 0, v[98:99]
	v_lshlrev_b64 v[42:43], 2, v[38:39]
	v_lshl_add_u64 v[38:39], v[66:67], 0, v[42:43]
	ds_read_b128 v[34:37], v138
	s_waitcnt vmcnt(15) lgkmcnt(0)
	v_pk_fma_f32 v[36:37], v[174:175], s[98:99], v[36:37] op_sel_hi:[1,0,1]
	v_pk_fma_f32 v[34:35], v[172:173], s[98:99], v[34:35] op_sel_hi:[1,0,1]
	v_lshl_add_u64 v[38:39], v[68:69], 0, v[42:43]
	global_store_dwordx4 v[38:39], v[34:37], off sc0 sc1
	v_lshl_add_u64 v[38:39], v[70:71], 0, v[100:101]
	v_lshlrev_b64 v[42:43], 2, v[38:39]
	v_lshl_add_u64 v[38:39], v[66:67], 0, v[42:43]
	ds_read_b128 v[34:37], v139
	s_waitcnt vmcnt(15) lgkmcnt(0)
	v_pk_fma_f32 v[36:37], v[178:179], s[98:99], v[36:37] op_sel_hi:[1,0,1]
	v_pk_fma_f32 v[34:35], v[176:177], s[98:99], v[34:35] op_sel_hi:[1,0,1]
	v_lshl_add_u64 v[38:39], v[68:69], 0, v[42:43]
	global_store_dwordx4 v[38:39], v[34:37], off sc0 sc1
	v_lshl_add_u64 v[38:39], v[70:71], 0, v[102:103]
	v_lshlrev_b64 v[42:43], 2, v[38:39]
	v_lshl_add_u64 v[38:39], v[66:67], 0, v[42:43]
	ds_read_b128 v[34:37], v140
	s_waitcnt vmcnt(15) lgkmcnt(0)
	v_pk_fma_f32 v[36:37], v[182:183], s[98:99], v[36:37] op_sel_hi:[1,0,1]
	v_pk_fma_f32 v[34:35], v[180:181], s[98:99], v[34:35] op_sel_hi:[1,0,1]
	v_lshl_add_u64 v[38:39], v[68:69], 0, v[42:43]
	global_store_dwordx4 v[38:39], v[34:37], off sc0 sc1
	s_waitcnt lgkmcnt(0)
	ds_write2_b32 v136, v30, v26 offset1:16
	v_mul_f32_e32 v26, v31, v0
	ds_write2_b32 v50, v22, v18 offset0:64 offset1:80
	v_mul_f32_e32 v18, v23, v0
	ds_write2_b32 v136, v26, v27 offset0:36 offset1:52
	v_mul_f32_e32 v26, v32, v0
	v_mul_f32_e32 v27, v28, v72
	ds_write2_b32 v50, v18, v19 offset0:100 offset1:116
	v_mul_f32_e32 v18, v24, v0
	v_mul_f32_e32 v19, v20, v72
	ds_write2_b32 v136, v26, v27 offset0:72 offset1:88
	v_mul_f32_e32 v26, v33, v0
	v_mul_f32_e32 v27, v29, v72
	ds_write2_b32 v50, v18, v19 offset0:136 offset1:152
	v_mul_f32_e32 v18, v25, v0
	v_mul_f32_e32 v19, v21, v72
	v_lshl_add_u64 v[22:23], v[70:71], 0, v[104:105]
	ds_write2_b32 v136, v26, v27 offset0:108 offset1:124
	ds_write2_b32 v50, v18, v19 offset0:172 offset1:188
	v_lshlrev_b64 v[26:27], 2, v[22:23]
	s_waitcnt lgkmcnt(0)
	v_lshl_add_u64 v[22:23], v[66:67], 0, v[26:27]
	ds_read_b128 v[18:21], v137
	s_waitcnt vmcnt(15) lgkmcnt(0)
	v_pk_fma_f32 v[20:21], v[186:187], s[98:99], v[20:21] op_sel_hi:[1,0,1]
	v_pk_fma_f32 v[18:19], v[184:185], s[98:99], v[18:19] op_sel_hi:[1,0,1]
	v_lshl_add_u64 v[22:23], v[68:69], 0, v[26:27]
	global_store_dwordx4 v[22:23], v[18:21], off sc0 sc1
	v_lshl_add_u64 v[22:23], v[70:71], 0, v[106:107]
	v_lshlrev_b64 v[26:27], 2, v[22:23]
	v_lshl_add_u64 v[22:23], v[66:67], 0, v[26:27]
	ds_read_b128 v[18:21], v138
	s_waitcnt vmcnt(15) lgkmcnt(0)
	v_pk_fma_f32 v[20:21], v[190:191], s[98:99], v[20:21] op_sel_hi:[1,0,1]
	v_pk_fma_f32 v[18:19], v[188:189], s[98:99], v[18:19] op_sel_hi:[1,0,1]
	v_lshl_add_u64 v[22:23], v[68:69], 0, v[26:27]
	global_store_dwordx4 v[22:23], v[18:21], off sc0 sc1
	v_lshl_add_u64 v[22:23], v[70:71], 0, v[108:109]
	v_lshlrev_b64 v[26:27], 2, v[22:23]
	v_lshl_add_u64 v[22:23], v[66:67], 0, v[26:27]
	ds_read_b128 v[18:21], v139
	s_waitcnt vmcnt(15) lgkmcnt(0)
	v_pk_fma_f32 v[20:21], v[194:195], s[98:99], v[20:21] op_sel_hi:[1,0,1]
	v_pk_fma_f32 v[18:19], v[192:193], s[98:99], v[18:19] op_sel_hi:[1,0,1]
	v_lshl_add_u64 v[22:23], v[68:69], 0, v[26:27]
	global_store_dwordx4 v[22:23], v[18:21], off sc0 sc1
	v_lshl_add_u64 v[22:23], v[70:71], 0, v[110:111]
	v_lshlrev_b64 v[26:27], 2, v[22:23]
	v_lshl_add_u64 v[22:23], v[66:67], 0, v[26:27]
	ds_read_b128 v[18:21], v140
	s_waitcnt vmcnt(15) lgkmcnt(0)
	v_pk_fma_f32 v[20:21], v[198:199], s[98:99], v[20:21] op_sel_hi:[1,0,1]
	v_pk_fma_f32 v[18:19], v[196:197], s[98:99], v[18:19] op_sel_hi:[1,0,1]
	v_lshl_add_u64 v[22:23], v[68:69], 0, v[26:27]
	global_store_dwordx4 v[22:23], v[18:21], off sc0 sc1
	s_waitcnt lgkmcnt(0)
	ds_write2_b32 v136, v14, v10 offset1:16
	v_mul_f32_e32 v10, v15, v0
	ds_write2_b32 v50, v6, v2 offset0:64 offset1:80
	v_mul_f32_e32 v2, v7, v0
	ds_write2_b32 v136, v10, v11 offset0:36 offset1:52
	v_mul_f32_e32 v10, v16, v0
	v_mul_f32_e32 v11, v12, v72
	ds_write2_b32 v50, v2, v3 offset0:100 offset1:116
	v_mul_f32_e32 v2, v8, v0
	v_mul_f32_e32 v3, v4, v72
	ds_write2_b32 v136, v10, v11 offset0:72 offset1:88
	v_mul_f32_e32 v10, v17, v0
	v_mul_f32_e32 v11, v13, v72
	ds_write2_b32 v50, v2, v3 offset0:136 offset1:152
	v_mul_f32_e32 v0, v9, v0
	v_mul_f32_e32 v2, v5, v72
	v_lshl_add_u64 v[6:7], v[70:71], 0, v[112:113]
	ds_write2_b32 v136, v10, v11 offset0:108 offset1:124
	ds_write2_b32 v50, v0, v2 offset0:172 offset1:188
	v_lshlrev_b64 v[10:11], 2, v[6:7]
	s_waitcnt lgkmcnt(0)
	v_lshl_add_u64 v[6:7], v[66:67], 0, v[10:11]
	ds_read_b128 v[2:5], v137
	s_waitcnt vmcnt(15) lgkmcnt(0)
	v_pk_fma_f32 v[4:5], v[202:203], s[98:99], v[4:5] op_sel_hi:[1,0,1]
	v_pk_fma_f32 v[2:3], v[200:201], s[98:99], v[2:3] op_sel_hi:[1,0,1]
	v_lshl_add_u64 v[6:7], v[68:69], 0, v[10:11]
	global_store_dwordx4 v[6:7], v[2:5], off sc0 sc1
	v_lshl_add_u64 v[6:7], v[70:71], 0, v[114:115]
	v_lshlrev_b64 v[10:11], 2, v[6:7]
	v_lshl_add_u64 v[6:7], v[66:67], 0, v[10:11]
	ds_read_b128 v[2:5], v138
	s_waitcnt vmcnt(15) lgkmcnt(0)
	v_pk_fma_f32 v[4:5], v[206:207], s[98:99], v[4:5] op_sel_hi:[1,0,1]
	v_pk_fma_f32 v[2:3], v[204:205], s[98:99], v[2:3] op_sel_hi:[1,0,1]
	v_lshl_add_u64 v[6:7], v[68:69], 0, v[10:11]
	global_store_dwordx4 v[6:7], v[2:5], off sc0 sc1
	v_lshl_add_u64 v[6:7], v[70:71], 0, v[116:117]
	v_lshlrev_b64 v[10:11], 2, v[6:7]
	v_lshl_add_u64 v[6:7], v[66:67], 0, v[10:11]
	ds_read_b128 v[2:5], v139
	s_waitcnt vmcnt(15) lgkmcnt(0)
	v_pk_fma_f32 v[4:5], v[210:211], s[98:99], v[4:5] op_sel_hi:[1,0,1]
	v_pk_fma_f32 v[2:3], v[208:209], s[98:99], v[2:3] op_sel_hi:[1,0,1]
	v_lshl_add_u64 v[6:7], v[68:69], 0, v[10:11]
	global_store_dwordx4 v[6:7], v[2:5], off sc0 sc1
	v_lshl_add_u64 v[6:7], v[70:71], 0, v[118:119]
	v_lshlrev_b64 v[10:11], 2, v[6:7]
	v_lshl_add_u64 v[6:7], v[66:67], 0, v[10:11]
	ds_read_b128 v[2:5], v140
	s_waitcnt vmcnt(15) lgkmcnt(0)
	v_pk_fma_f32 v[4:5], v[76:77], s[98:99], v[4:5] op_sel_hi:[1,0,1]
	v_pk_fma_f32 v[2:3], v[74:75], s[98:99], v[2:3] op_sel_hi:[1,0,1]
	v_lshl_add_u64 v[6:7], v[68:69], 0, v[10:11]
	global_store_dwordx4 v[6:7], v[2:5], off sc0 sc1
	s_waitcnt lgkmcnt(0)
	s_cbranch_vccnz .LBB0_45

.LBB0_301:
	s_or_b64 exec, exec, s[10:11]
	s_waitcnt vmcnt(0)
	v_mov_b32_e32 v98, v81
	v_mov_b32_e32 v99, v82
	v_mov_b32_e32 v100, v80
	v_mov_b32_e32 v101, v83
	v_pk_add_f32 v[98:99], v[98:99], v[100:101]
	s_waitcnt vmcnt(2)
	v_mov_b32_e32 v100, v77
	v_mov_b32_e32 v101, v78
	v_mov_b32_e32 v102, v76
	v_mov_b32_e32 v103, v79
	v_pk_add_f32 v[100:101], v[100:101], v[102:103]
	v_add_f32_e32 v0, v98, v99
	v_pk_add_f32 v[100:101], v[100:101], v[100:101] op_sel:[0,1] op_sel_hi:[1,0]
	v_add_f32_e32 v98, 0, v0
	s_waitcnt vmcnt(1)
	v_add_f32_e32 v102, v72, v73
	v_add_f32_e32 v104, v74, v75
	s_waitcnt vmcnt(0)
	v_mov_b32_e32 v99, v68
	v_mov_b32_e32 v101, v69
	v_mov_b32_e32 v103, v70
	v_mov_b32_e32 v105, v71
	v_pk_add_f32 v[98:99], v[98:99], v[100:101]
	v_pk_add_f32 v[100:101], v[102:103], v[104:105]
	s_mov_b32 s10, 0x800000
	v_pk_add_f32 v[98:99], v[98:99], v[100:101]
	s_nop 0
	v_add_f32_e32 v0, v98, v99
	s_nop 1
	v_add_f32_dpp v0, v0, v0 quad_perm:[1,0,3,2] row_mask:0xf bank_mask:0xf
	s_nop 1
	v_add_f32_dpp v0, v0, v0 quad_perm:[2,3,0,1] row_mask:0xf bank_mask:0xf
	s_nop 1
	v_add_f32_dpp v0, v0, v0 row_half_mirror row_mask:0xf bank_mask:0xf
	s_nop 1
	v_add_f32_dpp v0, v0, v0 row_mirror row_mask:0xf bank_mask:0xf
	s_nop 1
	v_readlane_b32 s100, v0, 0
	v_readlane_b32 s101, v0, 16
	v_readlane_b32 vcc_lo, v0, 32
	v_readlane_b32 vcc_hi, v0, 48
	s_nop 1
	v_mov_b32_e32 v97, s100
	v_add_f32_e32 v97, s101, v97
	v_add_f32_e32 v97, vcc_lo, v97
	v_add_f32_e32 v97, vcc_hi, v97
	v_fmamk_f32 v81, v97, 0xba800000, v81
	v_fmamk_f32 v80, v97, 0xba800000, v80
	v_fmamk_f32 v83, v97, 0xba800000, v83
	v_fmac_f32_e32 v82, 0xba800000, v97
	v_pk_mul_f32 v[98:99], v[82:83], v[82:83]
	v_pk_mul_f32 v[100:101], v[80:81], v[80:81]
	v_fmamk_f32 v77, v97, 0xba800000, v77
	v_fmamk_f32 v76, v97, 0xba800000, v76
	v_fmamk_f32 v79, v97, 0xba800000, v79
	v_pk_mov_b32 v[102:103], v[100:101], v[98:99] op_sel:[1,0]
	v_mov_b32_e32 v101, v99
	v_fmac_f32_e32 v78, 0xba800000, v97
	v_pk_add_f32 v[98:99], v[102:103], v[100:101]
	v_pk_mul_f32 v[100:101], v[78:79], v[78:79]
	v_pk_mul_f32 v[102:103], v[76:77], v[76:77]
	v_fmamk_f32 v72, v97, 0xba800000, v72
	v_pk_mov_b32 v[104:105], v[102:103], v[100:101] op_sel:[1,0]
	v_mov_b32_e32 v103, v101
	v_fmamk_f32 v73, v97, 0xba800000, v73
	v_fmac_f32_e32 v74, 0xba800000, v97
	v_mul_f32_e32 v0, v72, v72
	v_pk_add_f32 v[100:101], v[104:105], v[102:103]
	v_fmamk_f32 v75, v97, 0xba800000, v75
	v_pk_fma_f32 v[102:103], v[72:73], v[72:73], v[0:1] op_sel_hi:[1,1,0]
	v_mul_f32_e32 v0, v74, v74
	v_pk_add_f32 v[98:99], v[98:99], v[98:99] op_sel_hi:[0,1]
	v_pk_add_f32 v[100:101], v[100:101], v[100:101] op_sel_hi:[0,1]
	v_pk_fma_f32 v[104:105], v[74:75], v[74:75], v[0:1] op_sel_hi:[1,1,0]
	v_fmamk_f32 v71, v97, 0xba800000, v71
	v_fmamk_f32 v70, v97, 0xba800000, v70
	v_fmamk_f32 v69, v97, 0xba800000, v69
	v_fmac_f32_e32 v68, 0xba800000, v97
	v_mul_f32_e32 v102, v68, v68
	v_mul_f32_e32 v104, v69, v69
	v_mul_f32_e32 v98, v70, v70
	v_mul_f32_e32 v100, v71, v71
	v_pk_add_f32 v[102:103], v[102:103], v[104:105]
	v_pk_add_f32 v[98:99], v[98:99], v[100:101]
	s_nop 0
	v_pk_add_f32 v[98:99], v[102:103], v[98:99]
	s_nop 0
	v_add_f32_e32 v0, v98, v99
	s_nop 1
	v_add_f32_dpp v0, v0, v0 quad_perm:[1,0,3,2] row_mask:0xf bank_mask:0xf
	s_nop 1
	v_add_f32_dpp v0, v0, v0 quad_perm:[2,3,0,1] row_mask:0xf bank_mask:0xf
	s_nop 1
	v_add_f32_dpp v0, v0, v0 row_half_mirror row_mask:0xf bank_mask:0xf
	s_nop 1
	v_add_f32_dpp v0, v0, v0 row_mirror row_mask:0xf bank_mask:0xf
	s_nop 1
	v_readlane_b32 s100, v0, 0
	v_readlane_b32 s101, v0, 16
	v_readlane_b32 vcc_lo, v0, 32
	v_readlane_b32 vcc_hi, v0, 48
	s_nop 1
	v_mov_b32_e32 v0, s100
	v_add_f32_e32 v0, s101, v0
	v_add_f32_e32 v0, vcc_lo, v0
	v_add_f32_e32 v0, vcc_hi, v0
	v_fmamk_f32 v0, v0, 0x3a800000, v227
	v_mul_f32_e32 v97, 0x4b800000, v0
	v_cmp_gt_f32_e32 vcc, s10, v0
	s_nop 1
	v_cndmask_b32_e32 v0, v0, v97, vcc
	v_rsq_f32_e32 v0, v0
	s_nop 0
	v_mul_f32_e32 v97, 0x45800000, v0
	v_cndmask_b32_e32 v0, v0, v97, vcc
	v_pk_mul_f32 v[80:81], v[80:81], v[0:1] op_sel_hi:[1,0]
	v_pk_mul_f32 v[82:83], v[82:83], v[0:1] op_sel_hi:[1,0]
	v_pk_mul_f32 v[76:77], v[76:77], v[0:1] op_sel_hi:[1,0]
	v_pk_mul_f32 v[78:79], v[78:79], v[0:1] op_sel_hi:[1,0]
	v_pk_mul_f32 v[72:73], v[72:73], v[0:1] op_sel_hi:[1,0]
	v_pk_mul_f32 v[74:75], v[74:75], v[0:1] op_sel_hi:[1,0]
	v_pk_mul_f32 v[68:69], v[68:69], v[0:1] op_sel_hi:[1,0]
	v_pk_mul_f32 v[70:71], v[70:71], v[0:1] op_sel_hi:[1,0]
	v_pk_fma_f32 v[82:83], v[6:7], v[82:83], v[14:15]
	v_pk_fma_f32 v[80:81], v[4:5], v[80:81], v[12:13]
	v_pk_fma_f32 v[78:79], v[10:11], v[78:79], v[18:19]
	v_pk_fma_f32 v[76:77], v[8:9], v[76:77], v[16:17]
	v_pk_fma_f32 v[74:75], v[22:23], v[74:75], v[30:31]
	v_pk_fma_f32 v[72:73], v[20:21], v[72:73], v[28:29]
	v_pk_fma_f32 v[70:71], v[26:27], v[70:71], v[34:35]
	v_pk_fma_f32 v[68:69], v[24:25], v[68:69], v[32:33]
	s_andn2_b64 vcc, exec, s[4:5]
	global_store_dwordx4 v[88:89], v[80:83], off sc0 sc1 nt
	global_store_dwordx4 v[88:89], v[76:79], off offset:1024 sc0 sc1 nt
	global_store_dwordx4 v[88:89], v[72:75], off offset:2048 sc0 sc1 nt
	global_store_dwordx4 v[88:89], v[68:71], off offset:3072 sc0 sc1 nt
	s_cbranch_vccnz .LBB0_298
	v_mov_b32_e32 v88, v81
	v_mov_b32_e32 v89, v82
	v_mov_b32_e32 v98, v80
	v_mov_b32_e32 v99, v83
	v_pk_add_f32 v[88:89], v[88:89], v[98:99]
	v_mov_b32_e32 v98, v77
	v_mov_b32_e32 v99, v78
	v_mov_b32_e32 v100, v76
	v_mov_b32_e32 v101, v79
	v_pk_add_f32 v[98:99], v[98:99], v[100:101]
	v_add_f32_e32 v0, v88, v89
	v_pk_add_f32 v[98:99], v[98:99], v[98:99] op_sel_hi:[0,1]
	v_add_f32_e32 v89, 0, v0
	v_add_f32_e32 v101, v72, v73
	v_add_f32_e32 v103, v74, v75
	v_mov_b32_e32 v100, v68
	v_mov_b32_e32 v102, v69
	v_mov_b32_e32 v98, v70
	v_mov_b32_e32 v88, v71
	v_pk_add_f32 v[100:101], v[100:101], v[102:103]
	v_pk_add_f32 v[88:89], v[98:99], v[88:89]
	v_lshlrev_b64 v[2:3], 10, v[2:3]
	v_pk_add_f32 v[88:89], v[100:101], v[88:89]
	s_nop 0
	v_add_f32_e32 v0, v88, v89
	s_nop 1
	v_add_f32_dpp v0, v0, v0 quad_perm:[1,0,3,2] row_mask:0xf bank_mask:0xf
	s_nop 1
	v_add_f32_dpp v0, v0, v0 quad_perm:[2,3,0,1] row_mask:0xf bank_mask:0xf
	s_nop 1
	v_add_f32_dpp v0, v0, v0 row_half_mirror row_mask:0xf bank_mask:0xf
	s_nop 1
	v_add_f32_dpp v0, v0, v0 row_mirror row_mask:0xf bank_mask:0xf
	s_nop 1
	v_readlane_b32 s100, v0, 0
	v_readlane_b32 s101, v0, 16
	v_readlane_b32 vcc_lo, v0, 32
	v_readlane_b32 vcc_hi, v0, 48
	s_nop 1
	v_mov_b32_e32 v97, s100
	v_add_f32_e32 v97, s101, v97
	v_add_f32_e32 v97, vcc_lo, v97
	v_add_f32_e32 v97, vcc_hi, v97
	v_fmamk_f32 v81, v97, 0xba800000, v81
	v_fmamk_f32 v80, v97, 0xba800000, v80
	v_fmamk_f32 v83, v97, 0xba800000, v83
	v_fmac_f32_e32 v82, 0xba800000, v97
	v_pk_mul_f32 v[88:89], v[82:83], v[82:83]
	v_pk_mul_f32 v[98:99], v[80:81], v[80:81]
	v_fmamk_f32 v77, v97, 0xba800000, v77
	v_pk_mov_b32 v[100:101], v[98:99], v[88:89] op_sel:[1,0]
	v_mov_b32_e32 v99, v89
	v_fmamk_f32 v76, v97, 0xba800000, v76
	v_fmamk_f32 v79, v97, 0xba800000, v79
	v_fmac_f32_e32 v78, 0xba800000, v97
	v_pk_add_f32 v[88:89], v[100:101], v[98:99]
	v_pk_mul_f32 v[98:99], v[78:79], v[78:79]
	v_pk_mul_f32 v[100:101], v[76:77], v[76:77]
	v_fmamk_f32 v72, v97, 0xba800000, v72
	v_pk_mov_b32 v[102:103], v[100:101], v[98:99] op_sel:[1,0]
	v_mov_b32_e32 v101, v99
	v_fmamk_f32 v73, v97, 0xba800000, v73
	v_fmac_f32_e32 v74, 0xba800000, v97
	v_mul_f32_e32 v0, v72, v72
	v_pk_add_f32 v[98:99], v[102:103], v[100:101]
	v_fmamk_f32 v75, v97, 0xba800000, v75
	v_pk_fma_f32 v[100:101], v[72:73], v[72:73], v[0:1] op_sel_hi:[1,1,0]
	v_mul_f32_e32 v0, v74, v74
	v_pk_add_f32 v[88:89], v[88:89], v[88:89] op_sel_hi:[0,1]
	v_pk_add_f32 v[98:99], v[98:99], v[98:99] op_sel_hi:[0,1]
	v_pk_fma_f32 v[102:103], v[74:75], v[74:75], v[0:1] op_sel_hi:[1,1,0]
	v_fmamk_f32 v71, v97, 0xba800000, v71
	v_fmamk_f32 v70, v97, 0xba800000, v70
	v_fmamk_f32 v69, v97, 0xba800000, v69
	v_fmac_f32_e32 v68, 0xba800000, v97
	v_mul_f32_e32 v100, v68, v68
	v_mul_f32_e32 v102, v69, v69
	v_mul_f32_e32 v88, v70, v70
	v_mul_f32_e32 v98, v71, v71
	v_pk_add_f32 v[100:101], v[100:101], v[102:103]
	v_pk_add_f32 v[88:89], v[88:89], v[98:99]
	v_pk_add_f32 v[98:99], v[50:51], 1.0 op_sel_hi:[1,0]
	v_pk_add_f32 v[88:89], v[100:101], v[88:89]
	v_pk_add_f32 v[100:101], v[48:49], 1.0 op_sel_hi:[1,0]
	v_add_f32_e32 v0, v88, v89
	s_nop 1
	v_add_f32_dpp v0, v0, v0 quad_perm:[1,0,3,2] row_mask:0xf bank_mask:0xf
	s_nop 1
	v_add_f32_dpp v0, v0, v0 quad_perm:[2,3,0,1] row_mask:0xf bank_mask:0xf
	s_nop 1
	v_add_f32_dpp v0, v0, v0 row_half_mirror row_mask:0xf bank_mask:0xf
	s_nop 1
	v_add_f32_dpp v0, v0, v0 row_mirror row_mask:0xf bank_mask:0xf
	s_nop 1
	v_readlane_b32 s100, v0, 0
	v_readlane_b32 s101, v0, 16
	v_readlane_b32 vcc_lo, v0, 32
	v_readlane_b32 vcc_hi, v0, 48
	s_nop 1
	v_mov_b32_e32 v0, s100
	v_add_f32_e32 v0, s101, v0
	v_add_f32_e32 v0, vcc_lo, v0
	v_add_f32_e32 v0, vcc_hi, v0
	v_fmamk_f32 v0, v0, 0x3a800000, v227
	v_cmp_gt_f32_e32 vcc, s10, v0
	v_mul_f32_e32 v88, 0x4b800000, v0
	s_load_dwordx2 s[10:11], s[0:1], 0x148
	v_cndmask_b32_e32 v0, v0, v88, vcc
	v_rsq_f32_e32 v0, v0
	s_waitcnt lgkmcnt(0)
	v_lshl_add_u64 v[2:3], v[2:3], 1, s[10:11]
	v_mul_f32_e32 v88, 0x45800000, v0
	v_cndmask_b32_e32 v88, v0, v88, vcc
	v_pk_mul_f32 v[80:81], v[80:81], v[88:89] op_sel_hi:[1,0]
	v_pk_mul_f32 v[82:83], v[82:83], v[88:89] op_sel_hi:[1,0]
	v_lshlrev_b32_e32 v0, 1, v84
	v_pk_fma_f32 v[82:83], v[98:99], v[82:83], v[38:39]
	v_pk_fma_f32 v[80:81], v[100:101], v[80:81], v[36:37]
	v_lshl_add_u64 v[2:3], v[2:3], 0, v[0:1]
	v_cvt_pk_bf16_f32 v80, v80, v81
	v_cvt_pk_bf16_f32 v81, v82, v83
	global_store_dwordx2 v[2:3], v[80:81], off sc0 sc1
	v_pk_mul_f32 v[76:77], v[76:77], v[88:89] op_sel_hi:[1,0]
	v_pk_mul_f32 v[78:79], v[78:79], v[88:89] op_sel_hi:[1,0]
	v_pk_add_f32 v[80:81], v[42:43], 1.0 op_sel_hi:[1,0]
	v_pk_add_f32 v[82:83], v[40:41], 1.0 op_sel_hi:[1,0]
	v_pk_fma_f32 v[78:79], v[80:81], v[78:79], v[54:55]
	v_pk_fma_f32 v[76:77], v[82:83], v[76:77], v[52:53]
	v_pk_mul_f32 v[72:73], v[72:73], v[88:89] op_sel_hi:[1,0]
	v_cvt_pk_bf16_f32 v76, v76, v77
	v_cvt_pk_bf16_f32 v77, v78, v79
	global_store_dwordx2 v[2:3], v[76:77], off offset:512 sc0 sc1
	v_pk_mul_f32 v[74:75], v[74:75], v[88:89] op_sel_hi:[1,0]
	v_pk_add_f32 v[76:77], v[46:47], 1.0 op_sel_hi:[1,0]
	v_pk_add_f32 v[78:79], v[44:45], 1.0 op_sel_hi:[1,0]
	v_pk_fma_f32 v[74:75], v[76:77], v[74:75], v[58:59]
	v_pk_fma_f32 v[72:73], v[78:79], v[72:73], v[56:57]
	v_pk_mul_f32 v[68:69], v[68:69], v[88:89] op_sel_hi:[1,0]
	v_cvt_pk_bf16_f32 v72, v72, v73
	v_cvt_pk_bf16_f32 v73, v74, v75
	global_store_dwordx2 v[2:3], v[72:73], off offset:1024 sc0 sc1
	v_pk_mul_f32 v[70:71], v[70:71], v[88:89] op_sel_hi:[1,0]
	v_pk_add_f32 v[72:73], v[66:67], 1.0 op_sel_hi:[1,0]
	v_pk_add_f32 v[74:75], v[64:65], 1.0 op_sel_hi:[1,0]
	v_pk_fma_f32 v[70:71], v[72:73], v[70:71], v[62:63]
	v_pk_fma_f32 v[68:69], v[74:75], v[68:69], v[60:61]
	s_nop 0
	v_cvt_pk_bf16_f32 v68, v68, v69
	v_cvt_pk_bf16_f32 v69, v70, v71
	global_store_dwordx2 v[2:3], v[68:69], off offset:1536 sc0 sc1
	s_branch .LBB0_298
